# A hot-path layout with the attention code at the other 8-byte phase
# baseline (speedup 1.0000x reference)
; DI void attn_phase(const Params& P, char* shm) {
;     ...
;     __builtin_amdgcn_s_setprio(0);
.LBB0_438:
	s_nop 0
	s_nop 0
	s_setprio 0
	s_mov_b64 s[0:1], 0
